# norm1 (layer 1) token loop: chunk-load hoist with rebuilt offset pairs; all five norm phases now request chunk 1..3 parameters with chunk 0
# baseline (speedup 1.0000x reference)
.LBB0_1196:
	v_mul_hi_i32 v0, v14, s87
	v_lshrrev_b32_e32 v1, 31, v0
	v_ashrrev_i32_e32 v0, 9, v0
	v_add_u32_e32 v12, v0, v1
	v_mad_i32_i24 v1, v12, s88, v14
	v_cmp_gt_i32_e64 s[6:7], s83, v1
	v_cmp_lt_i32_e32 vcc, s89, v1
	s_and_saveexec_b64 s[0:1], vcc
	s_xor_b64 s[0:1], exec, s[0:1]
	v_mul_i32_i24_e32 v0, 0xfffff700, v12
	v_lshl_add_u32 v0, v12, 11, v0
	v_add3_u32 v0, v14, v0, s90
	s_or_saveexec_b64 s[0:1], s[0:1]
	v_mov_b64_e32 v[2:3], s[28:29]
	s_xor_b64 exec, exec, s[0:1]
	v_lshl_add_u32 v0, v12, 8, v1
	v_mov_b64_e32 v[2:3], s[66:67]
	s_or_b64 exec, exec, s[0:1]
	v_ashrrev_i32_e32 v1, 31, v0
	v_lshlrev_b64 v[0:1], 12, v[0:1]
	v_lshl_add_u64 v[0:1], v[2:3], 0, v[0:1]
	v_lshl_add_u64 v[2:3], v[0:1], 0, v[38:39]
	global_load_dwordx2 v[6:7], v[2:3], off
	global_load_dwordx2 v[4:5], v[2:3], off offset:512
	global_load_dwordx2 v[0:1], v[2:3], off offset:1024
	s_nop 0
	global_load_dwordx2 v[2:3], v[2:3], off offset:1536
	v_add_u32_e32 v67, s68, v14
	v_min_i32_e32 v66, 0x8fff, v67
	v_mul_hi_i32 v8, v66, s87
	v_lshrrev_b32_e32 v9, 31, v8
	v_ashrrev_i32_e32 v8, 9, v8
	v_add_u32_e32 v57, v8, v9
	v_mad_i32_i24 v9, v57, s88, v66
	v_cmp_gt_i32_e64 s[4:5], s83, v9
	v_cmp_lt_i32_e32 vcc, s89, v9
	s_and_saveexec_b64 s[0:1], vcc
	s_xor_b64 s[0:1], exec, s[0:1]
	v_lshlrev_b32_e32 v8, 11, v57
	v_add3_u32 v8, v8, v9, s90
	s_or_saveexec_b64 s[0:1], s[0:1]
	v_mov_b64_e32 v[10:11], s[28:29]
	s_xor_b64 exec, exec, s[0:1]
	v_lshl_add_u32 v8, v57, 8, v9
	v_mov_b64_e32 v[10:11], s[66:67]
	s_or_b64 exec, exec, s[0:1]
	v_ashrrev_i32_e32 v9, 31, v8
	v_lshlrev_b64 v[8:9], 12, v[8:9]
	v_lshl_add_u64 v[8:9], v[10:11], 0, v[8:9]
	v_lshl_add_u64 v[8:9], v[8:9], 0, v[38:39]
	global_load_dwordx2 v[74:75], v[8:9], off
	global_load_dwordx2 v[72:73], v[8:9], off offset:512
	global_load_dwordx2 v[68:69], v[8:9], off offset:1024
	global_load_dwordx2 v[70:71], v[8:9], off offset:1536
	v_add_u32_e32 v41, s27, v14
	v_min_i32_e32 v56, 0x8fff, v41
	v_mul_hi_i32 v8, v56, s87
	v_lshrrev_b32_e32 v9, 31, v8
	v_ashrrev_i32_e32 v8, 9, v8
	v_add_u32_e32 v29, v8, v9
	v_mad_i32_i24 v9, v29, s88, v56
	v_cmp_gt_i32_e64 s[2:3], s83, v9
	v_cmp_lt_i32_e32 vcc, s89, v9
	s_and_saveexec_b64 s[0:1], vcc
	s_xor_b64 s[0:1], exec, s[0:1]
	v_lshlrev_b32_e32 v8, 11, v29
	v_add3_u32 v8, v8, v9, s90
	s_or_saveexec_b64 s[0:1], s[0:1]
	v_mov_b64_e32 v[10:11], s[28:29]
	s_xor_b64 exec, exec, s[0:1]
	v_lshl_add_u32 v8, v29, 8, v9
	v_mov_b64_e32 v[10:11], s[66:67]
	s_or_b64 exec, exec, s[0:1]
	v_ashrrev_i32_e32 v9, 31, v8
	v_lshlrev_b64 v[8:9], 12, v[8:9]
	v_lshl_add_u64 v[8:9], v[10:11], 0, v[8:9]
	v_mov_b32_e32 v37, v13
	v_lshl_add_u64 v[8:9], v[8:9], 0, v[36:37]
	global_load_dwordx2 v[64:65], v[8:9], off
	global_load_dwordx2 v[62:63], v[8:9], off offset:512
	global_load_dwordx2 v[58:59], v[8:9], off offset:1024
	global_load_dwordx2 v[60:61], v[8:9], off offset:1536
	v_add_u32_e32 v25, s97, v14
	v_min_i32_e32 v40, 0x8fff, v25
	v_mul_hi_i32 v8, v40, s87
	v_lshrrev_b32_e32 v9, 31, v8
	v_ashrrev_i32_e32 v8, 9, v8
	v_add_u32_e32 v15, v8, v9
	v_mad_i32_i24 v9, v15, s88, v40
	v_cmp_gt_i32_e32 vcc, s83, v9
	v_cmp_lt_i32_e64 s[0:1], s89, v9
	s_and_saveexec_b64 s[8:9], s[0:1]
	s_xor_b64 s[0:1], exec, s[8:9]
	v_lshlrev_b32_e32 v8, 11, v15
	v_add3_u32 v8, v8, v9, s90
	s_or_saveexec_b64 s[0:1], s[0:1]
	v_mov_b64_e32 v[10:11], s[28:29]
	s_xor_b64 exec, exec, s[0:1]
	v_lshl_add_u32 v8, v15, 8, v9
	v_mov_b64_e32 v[10:11], s[66:67]
	s_or_b64 exec, exec, s[0:1]
	s_waitcnt vmcnt(11)
	v_and_b32_e32 v50, 0xffff0000, v6
	s_waitcnt vmcnt(10)
	v_and_b32_e32 v52, 0xffff0000, v4
	v_lshlrev_b32_e32 v90, 16, v6
	v_lshlrev_b32_e32 v55, 16, v5
	v_lshlrev_b32_e32 v54, 16, v4
	v_and_b32_e32 v53, 0xffff0000, v5
	v_mov_b32_e32 v4, v50
	v_mov_b32_e32 v5, v52
	v_lshlrev_b32_e32 v91, 16, v7
	s_waitcnt vmcnt(8)
	v_lshlrev_b32_e32 v81, 16, v2
	v_and_b32_e32 v79, 0xffff0000, v2
	v_lshlrev_b32_e32 v83, 16, v3
	v_and_b32_e32 v77, 0xffff0000, v3
	v_mov_b32_e32 v2, v90
	v_mov_b32_e32 v3, v54
	v_pk_mul_f32 v[4:5], v[4:5], v[4:5]
	v_and_b32_e32 v51, 0xffff0000, v7
	v_pk_fma_f32 v[2:3], v[2:3], v[2:3], v[4:5]
	v_mov_b32_e32 v4, v91
	v_mov_b32_e32 v5, v55
	v_and_b32_e32 v78, 0xffff0000, v0
	v_pk_fma_f32 v[2:3], v[4:5], v[4:5], v[2:3]
	v_mov_b32_e32 v4, v51
	v_mov_b32_e32 v5, v53
	v_lshlrev_b32_e32 v80, 16, v0
	v_pk_fma_f32 v[2:3], v[4:5], v[4:5], v[2:3]
	v_pk_mul_f32 v[4:5], v[78:79], v[78:79]
	v_lshlrev_b32_e32 v82, 16, v1
	v_pk_fma_f32 v[4:5], v[80:81], v[80:81], v[4:5]
	v_and_b32_e32 v76, 0xffff0000, v1
	v_pk_fma_f32 v[4:5], v[82:83], v[82:83], v[4:5]
	v_add_f32_e32 v2, v2, v3
	v_pk_fma_f32 v[4:5], v[76:77], v[76:77], v[4:5]
	v_ashrrev_i32_e32 v9, 31, v8
	v_add_f32_e32 v2, v2, v4
	v_add_f32_e32 v2, v2, v5
	v_lshlrev_b64 v[0:1], 12, v[8:9]
	v_lshl_add_u64 v[0:1], v[10:11], 0, v[0:1]
	v_add_f32_dpp v2, v2, v2 quad_perm:[1,0,3,2] row_mask:0xf bank_mask:0xf bound_ctrl:1
	v_mov_b32_e32 v37, v13
	v_lshl_add_u64 v[0:1], v[0:1], 0, v[36:37]
	v_add_f32_dpp v2, v2, v2 quad_perm:[2,3,0,1] row_mask:0xf bank_mask:0xf bound_ctrl:1
	global_load_dwordx2 v[48:49], v[0:1], off
	global_load_dwordx2 v[46:47], v[0:1], off offset:512
	global_load_dwordx2 v[42:43], v[0:1], off offset:1024
	global_load_dwordx2 v[44:45], v[0:1], off offset:1536
	v_add_f32_dpp v2, v2, v2 row_half_mirror row_mask:0xf bank_mask:0xf bound_ctrl:1
	v_cndmask_b32_e64 v0, v12, 16, s[6:7]
	v_mul_hi_i32_i24_e32 v1, 0x6000, v0
	v_add_f32_dpp v2, v2, v2 row_mirror row_mask:0xf bank_mask:0xf bound_ctrl:1
	v_mul_i32_i24_e32 v0, 0x6000, v0
	v_readlane_b32 s6, v2, 16
	v_readlane_b32 s7, v2, 48
	v_readlane_b32 s0, v2, 0
	v_readlane_b32 s1, v2, 32
	v_mov_b32_e32 v2, s6
	v_mov_b32_e32 v3, s7
	v_pk_add_f32 v[2:3], s[0:1], v[2:3]
	v_lshl_add_u64 v[0:1], s[64:65], 0, v[0:1]
	v_add_f32_e32 v2, v2, v3
	v_fmamk_f32 v2, v2, 0x3a800000, v17
	v_cmp_gt_f32_e64 s[0:1], s91, v2
	v_mul_f32_e32 v3, 0x4b800000, v2
	v_lshl_add_u64 v[88:89], v[0:1], 0, s[70:71]
	v_cndmask_b32_e64 v2, v2, v3, s[0:1]
	v_rsq_f32_e32 v2, v2
	v_lshlrev_b32_e32 v12, 2, v16
	v_lshl_add_u64 v[86:87], v[0:1], 0, v[12:13]
	v_mul_f32_e32 v3, 0x45800000, v2
	v_cndmask_b32_e64 v84, v2, v3, s[0:1]
	v_lshl_add_u64 v[2:3], v[88:89], 0, v[12:13]
	global_load_dwordx4 v[8:11], v[18:19], off
	s_nop 0
	global_load_dwordx4 v[0:3], v[2:3], off
	s_nop 0
	global_load_dwordx4 v[4:7], v[86:87], off
	global_load_dwordx4 v[96:99], v[22:23], off
	v_lshlrev_b32_e32 v132, 2, v20
	v_mov_b32_e32 v133, v13
	v_lshl_add_u64 v[134:135], v[88:89], 0, v[132:133]
	global_load_dwordx4 v[100:103], v[134:135], off
	global_load_dwordx4 v[104:107], v[86:87], off offset:1024
	global_load_dwordx4 v[108:111], v[26:27], off
	v_lshlrev_b32_e32 v132, 2, v24
	v_mov_b32_e32 v133, v13
	v_lshl_add_u64 v[134:135], v[88:89], 0, v[132:133]
	global_load_dwordx4 v[112:115], v[134:135], off
	global_load_dwordx4 v[116:119], v[86:87], off offset:2048
	global_load_dwordx4 v[120:123], v[30:31], off
	v_lshlrev_b32_e32 v132, 2, v28
	v_mov_b32_e32 v133, v13
	v_lshl_add_u64 v[134:135], v[88:89], 0, v[132:133]
	global_load_dwordx4 v[124:127], v[134:135], off
	global_load_dwordx4 v[128:131], v[86:87], off offset:3072
	v_pk_mul_f32 v[90:91], v[84:85], v[90:91] op_sel_hi:[0,1]
	v_pk_mul_f32 v[50:51], v[84:85], v[50:51] op_sel_hi:[0,1]
	v_pk_mul_f32 v[54:55], v[84:85], v[54:55] op_sel_hi:[0,1]
	v_pk_mul_f32 v[52:53], v[84:85], v[52:53] op_sel_hi:[0,1]
	v_cmp_gt_i32_e64 s[0:1], s86, v67
	s_waitcnt vmcnt(0) lgkmcnt(0)
	v_mov_b32_e32 v92, v8
	v_mov_b32_e32 v93, v10
	v_pk_mul_f32 v[90:91], v[92:93], v[90:91]
	v_mov_b32_e32 v93, v2
	v_mov_b32_e32 v10, v9
	v_mov_b32_e32 v2, v1
	v_mov_b32_e32 v92, v0
	v_mov_b32_e32 v95, v6
	v_pk_mul_f32 v[8:9], v[10:11], v[50:51]
	v_pk_add_f32 v[0:1], v[2:3], 1.0 op_sel_hi:[1,0]
	v_mov_b32_e32 v6, v5
	v_pk_add_f32 v[92:93], v[92:93], 1.0 op_sel_hi:[1,0]
	v_mov_b32_e32 v94, v4
	v_pk_fma_f32 v[0:1], v[0:1], v[8:9], v[6:7]
	v_pk_fma_f32 v[90:91], v[92:93], v[90:91], v[94:95]
	v_and_b32_sdwa v4, v1, v21 dst_sel:DWORD dst_unused:UNUSED_PAD src0_sel:WORD_1 src1_sel:DWORD
	v_and_b32_sdwa v5, v0, v21 dst_sel:DWORD dst_unused:UNUSED_PAD src0_sel:WORD_1 src1_sel:DWORD
	v_and_b32_sdwa v2, v91, v21 dst_sel:DWORD dst_unused:UNUSED_PAD src0_sel:WORD_1 src1_sel:DWORD
	v_and_b32_sdwa v3, v90, v21 dst_sel:DWORD dst_unused:UNUSED_PAD src0_sel:WORD_1 src1_sel:DWORD
	v_add3_u32 v1, v1, v4, s84
	v_add3_u32 v0, v0, v5, s84
	v_add3_u32 v3, v90, v3, s84
	v_add3_u32 v2, v91, v2, s84
	v_and_b32_e32 v1, 0xffff0000, v1
	v_and_b32_e32 v0, 0xffff0000, v0
	v_or_b32_sdwa v1, v1, v2 dst_sel:DWORD dst_unused:UNUSED_PAD src0_sel:DWORD src1_sel:WORD_1
	v_or_b32_sdwa v0, v0, v3 dst_sel:DWORD dst_unused:UNUSED_PAD src0_sel:DWORD src1_sel:WORD_1
	v_lshlrev_b32_e32 v50, 2, v20
	v_mov_b32_e32 v51, v13
	global_store_dwordx2 v[34:35], v[0:1], off
	v_lshl_add_u64 v[4:5], v[88:89], 0, v[50:51]
	s_nop 0
	s_nop 0
	s_waitcnt lgkmcnt(0)
	v_mov_b32_e32 v0, v96
	v_mov_b32_e32 v1, v97
	v_mov_b32_e32 v2, v98
	v_mov_b32_e32 v3, v99
	v_mov_b32_e32 v4, v100
	v_mov_b32_e32 v5, v101
	v_mov_b32_e32 v6, v102
	v_mov_b32_e32 v7, v103
	v_mov_b32_e32 v8, v104
	v_mov_b32_e32 v9, v105
	v_mov_b32_e32 v10, v106
	v_mov_b32_e32 v11, v107
	v_mov_b32_e32 v90, v0
	v_mov_b32_e32 v91, v2
	v_pk_mul_f32 v[54:55], v[54:55], v[90:91]
	v_mov_b32_e32 v91, v6
	v_mov_b32_e32 v2, v1
	v_mov_b32_e32 v6, v5
	v_mov_b32_e32 v90, v4
	v_mov_b32_e32 v93, v10
	v_pk_mul_f32 v[0:1], v[52:53], v[2:3]
	v_pk_add_f32 v[2:3], v[6:7], 1.0 op_sel_hi:[1,0]
	v_mov_b32_e32 v10, v9
	v_pk_add_f32 v[90:91], v[90:91], 1.0 op_sel_hi:[1,0]
	v_mov_b32_e32 v92, v8
	v_pk_fma_f32 v[0:1], v[0:1], v[2:3], v[10:11]
	v_pk_fma_f32 v[54:55], v[54:55], v[90:91], v[92:93]
	v_and_b32_sdwa v4, v1, v21 dst_sel:DWORD dst_unused:UNUSED_PAD src0_sel:WORD_1 src1_sel:DWORD
	v_and_b32_sdwa v5, v0, v21 dst_sel:DWORD dst_unused:UNUSED_PAD src0_sel:WORD_1 src1_sel:DWORD
	v_and_b32_sdwa v2, v55, v21 dst_sel:DWORD dst_unused:UNUSED_PAD src0_sel:WORD_1 src1_sel:DWORD
	v_and_b32_sdwa v3, v54, v21 dst_sel:DWORD dst_unused:UNUSED_PAD src0_sel:WORD_1 src1_sel:DWORD
	v_add3_u32 v1, v1, v4, s84
	v_add3_u32 v0, v0, v5, s84
	v_add3_u32 v3, v54, v3, s84
	v_add3_u32 v2, v55, v2, s84
	v_and_b32_e32 v1, 0xffff0000, v1
	v_and_b32_e32 v0, 0xffff0000, v0
	v_or_b32_sdwa v1, v1, v2 dst_sel:DWORD dst_unused:UNUSED_PAD src0_sel:DWORD src1_sel:WORD_1
	v_or_b32_sdwa v0, v0, v3 dst_sel:DWORD dst_unused:UNUSED_PAD src0_sel:DWORD src1_sel:WORD_1
	v_lshlrev_b32_e32 v52, 2, v24
	v_mov_b32_e32 v53, v13
	global_store_dwordx2 v[34:35], v[0:1], off offset:512
	v_lshl_add_u64 v[4:5], v[88:89], 0, v[52:53]
	s_nop 0
	s_nop 0
	v_mov_b32_e32 v54, v80
	v_mov_b32_e32 v55, v82
	v_pk_mul_f32 v[54:55], v[84:85], v[54:55] op_sel_hi:[0,1]
	v_mov_b32_e32 v82, v81
	v_pk_mul_f32 v[80:81], v[84:85], v[82:83] op_sel_hi:[0,1]
	s_waitcnt lgkmcnt(0)
	v_mov_b32_e32 v0, v108
	v_mov_b32_e32 v1, v109
	v_mov_b32_e32 v2, v110
	v_mov_b32_e32 v3, v111
	v_mov_b32_e32 v4, v112
	v_mov_b32_e32 v5, v113
	v_mov_b32_e32 v6, v114
	v_mov_b32_e32 v7, v115
	v_mov_b32_e32 v8, v116
	v_mov_b32_e32 v9, v117
	v_mov_b32_e32 v10, v118
	v_mov_b32_e32 v11, v119
	v_mov_b32_e32 v90, v0
	v_mov_b32_e32 v91, v2
	v_pk_mul_f32 v[54:55], v[54:55], v[90:91]
	v_mov_b32_e32 v90, v4
	v_mov_b32_e32 v91, v6
	v_pk_add_f32 v[90:91], v[90:91], 1.0 op_sel_hi:[1,0]
	v_mov_b32_e32 v92, v8
	v_mov_b32_e32 v93, v10
	v_pk_fma_f32 v[54:55], v[54:55], v[90:91], v[92:93]
	v_mov_b32_e32 v90, v78
	v_mov_b32_e32 v91, v76
	v_pk_mul_f32 v[90:91], v[84:85], v[90:91] op_sel_hi:[0,1]
	v_mov_b32_e32 v2, v1
	v_mov_b32_e32 v6, v5
	v_pk_mul_f32 v[0:1], v[90:91], v[2:3]
	v_pk_add_f32 v[2:3], v[6:7], 1.0 op_sel_hi:[1,0]
	v_mov_b32_e32 v10, v9
	v_pk_fma_f32 v[0:1], v[0:1], v[2:3], v[10:11]
	v_and_b32_sdwa v2, v55, v21 dst_sel:DWORD dst_unused:UNUSED_PAD src0_sel:WORD_1 src1_sel:DWORD
	v_and_b32_sdwa v4, v1, v21 dst_sel:DWORD dst_unused:UNUSED_PAD src0_sel:WORD_1 src1_sel:DWORD
	v_and_b32_sdwa v5, v0, v21 dst_sel:DWORD dst_unused:UNUSED_PAD src0_sel:WORD_1 src1_sel:DWORD
	v_and_b32_sdwa v3, v54, v21 dst_sel:DWORD dst_unused:UNUSED_PAD src0_sel:WORD_1 src1_sel:DWORD
	v_add3_u32 v1, v1, v4, s84
	v_add3_u32 v0, v0, v5, s84
	v_add3_u32 v3, v54, v3, s84
	v_add3_u32 v2, v55, v2, s84
	v_and_b32_e32 v1, 0xffff0000, v1
	v_and_b32_e32 v0, 0xffff0000, v0
	v_or_b32_sdwa v1, v1, v2 dst_sel:DWORD dst_unused:UNUSED_PAD src0_sel:DWORD src1_sel:WORD_1
	v_or_b32_sdwa v0, v0, v3 dst_sel:DWORD dst_unused:UNUSED_PAD src0_sel:DWORD src1_sel:WORD_1
	v_lshlrev_b32_e32 v54, 2, v28
	v_mov_b32_e32 v55, v13
	global_store_dwordx2 v[34:35], v[0:1], off offset:1024
	v_lshl_add_u64 v[4:5], v[88:89], 0, v[54:55]
	s_nop 0
	s_nop 0
	v_mov_b32_e32 v76, v79
	v_pk_mul_f32 v[76:77], v[84:85], v[76:77] op_sel_hi:[0,1]
	s_waitcnt lgkmcnt(0)
	v_mov_b32_e32 v0, v120
	v_mov_b32_e32 v1, v121
	v_mov_b32_e32 v2, v122
	v_mov_b32_e32 v3, v123
	v_mov_b32_e32 v4, v124
	v_mov_b32_e32 v5, v125
	v_mov_b32_e32 v6, v126
	v_mov_b32_e32 v7, v127
	v_mov_b32_e32 v8, v128
	v_mov_b32_e32 v9, v129
	v_mov_b32_e32 v10, v130
	v_mov_b32_e32 v11, v131
	v_mov_b32_e32 v82, v0
	v_mov_b32_e32 v83, v2
	v_pk_mul_f32 v[80:81], v[80:81], v[82:83]
	v_mov_b32_e32 v83, v6
	v_mov_b32_e32 v2, v1
	v_mov_b32_e32 v6, v5
	v_mov_b32_e32 v82, v4
	v_mov_b32_e32 v87, v10
	v_pk_mul_f32 v[0:1], v[76:77], v[2:3]
	v_pk_add_f32 v[2:3], v[6:7], 1.0 op_sel_hi:[1,0]
	v_mov_b32_e32 v10, v9
	v_pk_add_f32 v[82:83], v[82:83], 1.0 op_sel_hi:[1,0]
	v_mov_b32_e32 v86, v8
	v_pk_fma_f32 v[0:1], v[0:1], v[2:3], v[10:11]
	v_pk_fma_f32 v[80:81], v[80:81], v[82:83], v[86:87]
	v_and_b32_sdwa v4, v1, v21 dst_sel:DWORD dst_unused:UNUSED_PAD src0_sel:WORD_1 src1_sel:DWORD
	v_and_b32_sdwa v5, v0, v21 dst_sel:DWORD dst_unused:UNUSED_PAD src0_sel:WORD_1 src1_sel:DWORD
	v_and_b32_sdwa v2, v81, v21 dst_sel:DWORD dst_unused:UNUSED_PAD src0_sel:WORD_1 src1_sel:DWORD
	v_and_b32_sdwa v3, v80, v21 dst_sel:DWORD dst_unused:UNUSED_PAD src0_sel:WORD_1 src1_sel:DWORD
	v_add3_u32 v1, v1, v4, s84
	v_add3_u32 v0, v0, v5, s84
	v_add3_u32 v3, v80, v3, s84
	v_add3_u32 v2, v81, v2, s84
	v_and_b32_e32 v1, 0xffff0000, v1
	v_and_b32_e32 v0, 0xffff0000, v0
	v_or_b32_sdwa v1, v1, v2 dst_sel:DWORD dst_unused:UNUSED_PAD src0_sel:DWORD src1_sel:WORD_1
	v_or_b32_sdwa v0, v0, v3 dst_sel:DWORD dst_unused:UNUSED_PAD src0_sel:DWORD src1_sel:WORD_1
	global_store_dwordx2 v[34:35], v[0:1], off offset:1536
	s_and_saveexec_b64 s[6:7], s[0:1]
	s_cbranch_execz .LBB0_1195
	v_and_b32_e32 v84, 0xffff0000, v74
	v_and_b32_e32 v80, 0xffff0000, v72
	v_lshlrev_b32_e32 v86, 16, v74
	v_lshlrev_b32_e32 v82, 16, v72
	v_mov_b32_e32 v4, v84
	v_mov_b32_e32 v5, v80
	v_lshlrev_b32_e32 v87, 16, v75
	v_lshlrev_b32_e32 v83, 16, v73
	v_mov_b32_e32 v2, v86
	v_mov_b32_e32 v3, v82
	v_pk_mul_f32 v[4:5], v[4:5], v[4:5]
	v_and_b32_e32 v85, 0xffff0000, v75
	v_and_b32_e32 v81, 0xffff0000, v73
	v_pk_fma_f32 v[2:3], v[2:3], v[2:3], v[4:5]
	v_mov_b32_e32 v4, v87
	v_mov_b32_e32 v5, v83
	v_and_b32_e32 v73, 0xffff0000, v70
	v_and_b32_e32 v72, 0xffff0000, v68
	v_pk_fma_f32 v[2:3], v[4:5], v[4:5], v[2:3]
	v_mov_b32_e32 v4, v85
	v_mov_b32_e32 v5, v81
	v_lshlrev_b32_e32 v75, 16, v70
	v_lshlrev_b32_e32 v74, 16, v68
	v_pk_fma_f32 v[2:3], v[4:5], v[4:5], v[2:3]
	v_pk_mul_f32 v[4:5], v[72:73], v[72:73]
	v_lshlrev_b32_e32 v77, 16, v71
	v_lshlrev_b32_e32 v76, 16, v69
	v_pk_fma_f32 v[4:5], v[74:75], v[74:75], v[4:5]
	v_and_b32_e32 v71, 0xffff0000, v71
	v_and_b32_e32 v70, 0xffff0000, v69
	v_pk_fma_f32 v[4:5], v[76:77], v[76:77], v[4:5]
	v_add_f32_e32 v2, v2, v3
	v_pk_fma_f32 v[4:5], v[70:71], v[70:71], v[4:5]
	v_cndmask_b32_e64 v0, v57, 16, s[4:5]
	v_add_f32_e32 v2, v2, v4
	v_add_f32_e32 v2, v2, v5
	v_mul_hi_i32_i24_e32 v1, 0x6000, v0
	v_mul_i32_i24_e32 v0, 0x6000, v0
	v_add_f32_dpp v2, v2, v2 quad_perm:[1,0,3,2] row_mask:0xf bank_mask:0xf bound_ctrl:1
	v_lshl_add_u64 v[0:1], s[64:65], 0, v[0:1]
	v_lshl_add_u64 v[78:79], v[0:1], 0, s[70:71]
	v_add_f32_dpp v2, v2, v2 quad_perm:[2,3,0,1] row_mask:0xf bank_mask:0xf bound_ctrl:1
	v_ashrrev_i32_e32 v67, 31, v66
	v_lshlrev_b64 v[88:89], 11, v[66:67]
	v_add_f32_dpp v2, v2, v2 row_half_mirror row_mask:0xf bank_mask:0xf bound_ctrl:1
	v_lshl_add_u64 v[66:67], v[0:1], 0, v[12:13]
	s_nop 0
	v_add_f32_dpp v2, v2, v2 row_mirror row_mask:0xf bank_mask:0xf bound_ctrl:1
	s_nop 0
	v_readlane_b32 s4, v2, 16
	v_readlane_b32 s5, v2, 48
	v_readlane_b32 s0, v2, 0
	v_readlane_b32 s1, v2, 32
	v_mov_b32_e32 v2, s4
	v_mov_b32_e32 v3, s5
	v_pk_add_f32 v[2:3], s[0:1], v[2:3]
	s_nop 0
	v_add_f32_e32 v2, v2, v3
	v_fmamk_f32 v2, v2, 0x3a800000, v17
	v_cmp_gt_f32_e64 s[0:1], s91, v2
	v_mul_f32_e32 v3, 0x4b800000, v2
	s_nop 0
	v_cndmask_b32_e64 v2, v2, v3, s[0:1]
	v_rsq_f32_e32 v2, v2
	s_nop 0
	v_mul_f32_e32 v3, 0x45800000, v2
	v_cndmask_b32_e64 v68, v2, v3, s[0:1]
	v_lshl_add_u64 v[2:3], v[78:79], 0, v[12:13]
	global_load_dwordx4 v[8:11], v[18:19], off
	global_load_dwordx4 v[4:7], v[2:3], off
	s_nop 0
	global_load_dwordx4 v[0:3], v[66:67], off
	global_load_dwordx4 v[96:99], v[22:23], off
	v_mov_b32_e32 v132, v50
	v_mov_b32_e32 v133, v13
	v_lshl_add_u64 v[134:135], v[78:79], 0, v[132:133]
	global_load_dwordx4 v[100:103], v[134:135], off
	global_load_dwordx4 v[104:107], v[66:67], off offset:1024
	global_load_dwordx4 v[108:111], v[26:27], off
	v_mov_b32_e32 v132, v52
	v_mov_b32_e32 v133, v13
	v_lshl_add_u64 v[134:135], v[78:79], 0, v[132:133]
	global_load_dwordx4 v[112:115], v[134:135], off
	global_load_dwordx4 v[116:119], v[66:67], off offset:2048
	global_load_dwordx4 v[120:123], v[30:31], off
	v_mov_b32_e32 v132, v54
	v_mov_b32_e32 v133, v13
	v_lshl_add_u64 v[134:135], v[78:79], 0, v[132:133]
	global_load_dwordx4 v[124:127], v[134:135], off
	global_load_dwordx4 v[128:131], v[66:67], off offset:3072
	v_pk_mul_f32 v[86:87], v[68:69], v[86:87] op_sel_hi:[0,1]
	v_pk_mul_f32 v[84:85], v[68:69], v[84:85] op_sel_hi:[0,1]
	v_pk_mul_f32 v[80:81], v[68:69], v[80:81] op_sel_hi:[0,1]
	v_cmp_gt_i32_e64 s[0:1], s86, v41
	s_waitcnt vmcnt(0) lgkmcnt(0)
	v_mov_b32_e32 v90, v8
	v_mov_b32_e32 v91, v10
	v_pk_mul_f32 v[86:87], v[90:91], v[86:87]
	v_mov_b32_e32 v90, v4
	v_mov_b32_e32 v91, v6
	v_pk_add_f32 v[90:91], v[90:91], 1.0 op_sel_hi:[1,0]
	v_mov_b32_e32 v92, v0
	v_mov_b32_e32 v93, v2
	v_mov_b32_e32 v10, v9
	v_mov_b32_e32 v6, v5
	v_pk_fma_f32 v[86:87], v[90:91], v[86:87], v[92:93]
	v_pk_mul_f32 v[8:9], v[10:11], v[84:85]
	v_pk_add_f32 v[4:5], v[6:7], 1.0 op_sel_hi:[1,0]
	v_mov_b32_e32 v2, v1
	v_pk_fma_f32 v[0:1], v[4:5], v[8:9], v[2:3]
	v_and_b32_sdwa v3, v86, v21 dst_sel:DWORD dst_unused:UNUSED_PAD src0_sel:WORD_1 src1_sel:DWORD
	v_add3_u32 v4, v86, v3, s84
	v_and_b32_sdwa v3, v1, v21 dst_sel:DWORD dst_unused:UNUSED_PAD src0_sel:WORD_1 src1_sel:DWORD
	v_and_b32_sdwa v5, v0, v21 dst_sel:DWORD dst_unused:UNUSED_PAD src0_sel:WORD_1 src1_sel:DWORD
	v_and_b32_sdwa v2, v87, v21 dst_sel:DWORD dst_unused:UNUSED_PAD src0_sel:WORD_1 src1_sel:DWORD
	v_add3_u32 v1, v1, v3, s84
	v_add3_u32 v0, v0, v5, s84
	v_add3_u32 v2, v87, v2, s84
	v_and_b32_e32 v1, 0xffff0000, v1
	v_and_b32_e32 v0, 0xffff0000, v0
	v_or_b32_sdwa v3, v1, v2 dst_sel:DWORD dst_unused:UNUSED_PAD src0_sel:DWORD src1_sel:WORD_1
	v_or_b32_sdwa v2, v0, v4 dst_sel:DWORD dst_unused:UNUSED_PAD src0_sel:DWORD src1_sel:WORD_1
	v_lshl_add_u64 v[0:1], v[32:33], 0, v[88:89]
	global_store_dwordx2 v[0:1], v[2:3], off
	v_lshl_add_u64 v[6:7], v[78:79], 0, v[50:51]
	s_nop 0
	s_nop 0
	v_pk_mul_f32 v[10:11], v[68:69], v[82:83] op_sel_hi:[0,1]
	s_waitcnt lgkmcnt(0)
	v_mov_b32_e32 v2, v96
	v_mov_b32_e32 v3, v97
	v_mov_b32_e32 v4, v98
	v_mov_b32_e32 v5, v99
	v_mov_b32_e32 v6, v100
	v_mov_b32_e32 v7, v101
	v_mov_b32_e32 v8, v102
	v_mov_b32_e32 v9, v103
	v_mov_b32_e32 v84, v104
	v_mov_b32_e32 v85, v105
	v_mov_b32_e32 v86, v106
	v_mov_b32_e32 v87, v107
	v_mov_b32_e32 v82, v2
	v_mov_b32_e32 v83, v4
	v_pk_mul_f32 v[10:11], v[10:11], v[82:83]
	v_mov_b32_e32 v83, v8
	v_mov_b32_e32 v4, v3
	v_mov_b32_e32 v8, v7
	v_mov_b32_e32 v82, v6
	v_mov_b32_e32 v89, v86
	v_pk_mul_f32 v[2:3], v[80:81], v[4:5]
	v_pk_add_f32 v[4:5], v[8:9], 1.0 op_sel_hi:[1,0]
	v_mov_b32_e32 v86, v85
	v_pk_add_f32 v[82:83], v[82:83], 1.0 op_sel_hi:[1,0]
	v_mov_b32_e32 v88, v84
	v_pk_fma_f32 v[2:3], v[2:3], v[4:5], v[86:87]
	v_pk_fma_f32 v[10:11], v[10:11], v[82:83], v[88:89]
	v_and_b32_sdwa v6, v3, v21 dst_sel:DWORD dst_unused:UNUSED_PAD src0_sel:WORD_1 src1_sel:DWORD
	v_and_b32_sdwa v7, v2, v21 dst_sel:DWORD dst_unused:UNUSED_PAD src0_sel:WORD_1 src1_sel:DWORD
	v_and_b32_sdwa v4, v11, v21 dst_sel:DWORD dst_unused:UNUSED_PAD src0_sel:WORD_1 src1_sel:DWORD
	v_and_b32_sdwa v5, v10, v21 dst_sel:DWORD dst_unused:UNUSED_PAD src0_sel:WORD_1 src1_sel:DWORD
	v_add3_u32 v3, v3, v6, s84
	v_add3_u32 v2, v2, v7, s84
	v_add3_u32 v5, v10, v5, s84
	v_add3_u32 v4, v11, v4, s84
	v_and_b32_e32 v3, 0xffff0000, v3
	v_and_b32_e32 v2, 0xffff0000, v2
	v_or_b32_sdwa v3, v3, v4 dst_sel:DWORD dst_unused:UNUSED_PAD src0_sel:DWORD src1_sel:WORD_1
	v_or_b32_sdwa v2, v2, v5 dst_sel:DWORD dst_unused:UNUSED_PAD src0_sel:DWORD src1_sel:WORD_1
	global_store_dwordx2 v[0:1], v[2:3], off offset:512
	v_lshl_add_u64 v[6:7], v[78:79], 0, v[52:53]
	s_nop 0
	s_nop 0
	v_mov_b32_e32 v10, v74
	v_mov_b32_e32 v11, v76
	v_pk_mul_f32 v[10:11], v[68:69], v[10:11] op_sel_hi:[0,1]
	v_mov_b32_e32 v76, v75
	s_waitcnt lgkmcnt(0)
	v_mov_b32_e32 v2, v108
	v_mov_b32_e32 v3, v109
	v_mov_b32_e32 v4, v110
	v_mov_b32_e32 v5, v111
	v_mov_b32_e32 v6, v112
	v_mov_b32_e32 v7, v113
	v_mov_b32_e32 v8, v114
	v_mov_b32_e32 v9, v115
	v_mov_b32_e32 v80, v116
	v_mov_b32_e32 v81, v117
	v_mov_b32_e32 v82, v118
	v_mov_b32_e32 v83, v119
	v_mov_b32_e32 v84, v2
	v_mov_b32_e32 v85, v4
	v_pk_mul_f32 v[10:11], v[10:11], v[84:85]
	v_mov_b32_e32 v84, v6
	v_mov_b32_e32 v85, v8
	v_pk_add_f32 v[84:85], v[84:85], 1.0 op_sel_hi:[1,0]
	v_mov_b32_e32 v86, v80
	v_mov_b32_e32 v87, v82
	v_pk_fma_f32 v[10:11], v[10:11], v[84:85], v[86:87]
	v_mov_b32_e32 v84, v72
	v_mov_b32_e32 v85, v70
	v_pk_mul_f32 v[84:85], v[68:69], v[84:85] op_sel_hi:[0,1]
	v_mov_b32_e32 v4, v3
	v_mov_b32_e32 v8, v7
	v_pk_mul_f32 v[2:3], v[84:85], v[4:5]
	v_pk_add_f32 v[4:5], v[8:9], 1.0 op_sel_hi:[1,0]
	v_mov_b32_e32 v82, v81
	v_pk_fma_f32 v[2:3], v[2:3], v[4:5], v[82:83]
	v_and_b32_sdwa v4, v11, v21 dst_sel:DWORD dst_unused:UNUSED_PAD src0_sel:WORD_1 src1_sel:DWORD
	v_and_b32_sdwa v6, v3, v21 dst_sel:DWORD dst_unused:UNUSED_PAD src0_sel:WORD_1 src1_sel:DWORD
	v_and_b32_sdwa v7, v2, v21 dst_sel:DWORD dst_unused:UNUSED_PAD src0_sel:WORD_1 src1_sel:DWORD
	v_and_b32_sdwa v5, v10, v21 dst_sel:DWORD dst_unused:UNUSED_PAD src0_sel:WORD_1 src1_sel:DWORD
	v_add3_u32 v3, v3, v6, s84
	v_add3_u32 v2, v2, v7, s84
	v_add3_u32 v5, v10, v5, s84
	v_add3_u32 v4, v11, v4, s84
	v_and_b32_e32 v3, 0xffff0000, v3
	v_and_b32_e32 v2, 0xffff0000, v2
	v_or_b32_sdwa v3, v3, v4 dst_sel:DWORD dst_unused:UNUSED_PAD src0_sel:DWORD src1_sel:WORD_1
	v_or_b32_sdwa v2, v2, v5 dst_sel:DWORD dst_unused:UNUSED_PAD src0_sel:DWORD src1_sel:WORD_1
	global_store_dwordx2 v[0:1], v[2:3], off offset:1024
	v_lshl_add_u64 v[6:7], v[78:79], 0, v[54:55]
	s_nop 0
	s_nop 0
	v_pk_mul_f32 v[10:11], v[68:69], v[76:77] op_sel_hi:[0,1]
	v_mov_b32_e32 v70, v73
	s_waitcnt lgkmcnt(0)
	v_mov_b32_e32 v2, v120
	v_mov_b32_e32 v3, v121
	v_mov_b32_e32 v4, v122
	v_mov_b32_e32 v5, v123
	v_mov_b32_e32 v6, v124
	v_mov_b32_e32 v7, v125
	v_mov_b32_e32 v8, v126
	v_mov_b32_e32 v9, v127
	v_mov_b32_e32 v78, v128
	v_mov_b32_e32 v79, v129
	v_mov_b32_e32 v80, v130
	v_mov_b32_e32 v81, v131
	v_mov_b32_e32 v66, v2
	v_mov_b32_e32 v67, v4
	v_pk_mul_f32 v[10:11], v[10:11], v[66:67]
	v_mov_b32_e32 v66, v6
	v_mov_b32_e32 v67, v8
	v_pk_add_f32 v[66:67], v[66:67], 1.0 op_sel_hi:[1,0]
	v_mov_b32_e32 v74, v78
	v_mov_b32_e32 v75, v80
	v_pk_fma_f32 v[10:11], v[10:11], v[66:67], v[74:75]
	v_pk_mul_f32 v[66:67], v[68:69], v[70:71] op_sel_hi:[0,1]
	v_mov_b32_e32 v4, v3
	v_mov_b32_e32 v8, v7
	v_pk_mul_f32 v[2:3], v[66:67], v[4:5]
	v_pk_add_f32 v[4:5], v[8:9], 1.0 op_sel_hi:[1,0]
	v_mov_b32_e32 v80, v79
	v_pk_fma_f32 v[2:3], v[2:3], v[4:5], v[80:81]
	v_and_b32_sdwa v4, v11, v21 dst_sel:DWORD dst_unused:UNUSED_PAD src0_sel:WORD_1 src1_sel:DWORD
	v_and_b32_sdwa v6, v3, v21 dst_sel:DWORD dst_unused:UNUSED_PAD src0_sel:WORD_1 src1_sel:DWORD
	v_and_b32_sdwa v7, v2, v21 dst_sel:DWORD dst_unused:UNUSED_PAD src0_sel:WORD_1 src1_sel:DWORD
	v_and_b32_sdwa v5, v10, v21 dst_sel:DWORD dst_unused:UNUSED_PAD src0_sel:WORD_1 src1_sel:DWORD
	v_add3_u32 v3, v3, v6, s84
	v_add3_u32 v2, v2, v7, s84
	v_add3_u32 v5, v10, v5, s84
	v_add3_u32 v4, v11, v4, s84
	v_and_b32_e32 v3, 0xffff0000, v3
	v_and_b32_e32 v2, 0xffff0000, v2
	v_or_b32_sdwa v3, v3, v4 dst_sel:DWORD dst_unused:UNUSED_PAD src0_sel:DWORD src1_sel:WORD_1
	v_or_b32_sdwa v2, v2, v5 dst_sel:DWORD dst_unused:UNUSED_PAD src0_sel:DWORD src1_sel:WORD_1
	global_store_dwordx2 v[0:1], v[2:3], off offset:1536
	s_and_b64 exec, exec, s[0:1]
	s_cbranch_execz .LBB0_1195
	v_and_b32_e32 v74, 0xffff0000, v64
	v_and_b32_e32 v70, 0xffff0000, v62
	v_lshlrev_b32_e32 v76, 16, v64
	v_lshlrev_b32_e32 v72, 16, v62
	v_mov_b32_e32 v4, v74
	v_mov_b32_e32 v5, v70
	v_lshlrev_b32_e32 v77, 16, v65
	v_lshlrev_b32_e32 v73, 16, v63
	v_mov_b32_e32 v2, v76
	v_mov_b32_e32 v3, v72
	v_pk_mul_f32 v[4:5], v[4:5], v[4:5]
	v_and_b32_e32 v75, 0xffff0000, v65
	v_and_b32_e32 v71, 0xffff0000, v63
	v_pk_fma_f32 v[2:3], v[2:3], v[2:3], v[4:5]
	v_mov_b32_e32 v4, v77
	v_mov_b32_e32 v5, v73
	v_and_b32_e32 v63, 0xffff0000, v60
	v_and_b32_e32 v62, 0xffff0000, v58
	v_pk_fma_f32 v[2:3], v[4:5], v[4:5], v[2:3]
	v_mov_b32_e32 v4, v75
	v_mov_b32_e32 v5, v71
	v_lshlrev_b32_e32 v65, 16, v60
	v_lshlrev_b32_e32 v64, 16, v58
	v_pk_fma_f32 v[2:3], v[4:5], v[4:5], v[2:3]
	v_pk_mul_f32 v[4:5], v[62:63], v[62:63]
	v_lshlrev_b32_e32 v67, 16, v61
	v_lshlrev_b32_e32 v66, 16, v59
	v_pk_fma_f32 v[4:5], v[64:65], v[64:65], v[4:5]
	v_and_b32_e32 v61, 0xffff0000, v61
	v_and_b32_e32 v60, 0xffff0000, v59
	v_pk_fma_f32 v[4:5], v[66:67], v[66:67], v[4:5]
	v_add_f32_e32 v2, v2, v3
	v_pk_fma_f32 v[4:5], v[60:61], v[60:61], v[4:5]
	v_cndmask_b32_e64 v0, v29, 16, s[2:3]
	v_add_f32_e32 v2, v2, v4
	v_add_f32_e32 v2, v2, v5
	v_mul_hi_i32_i24_e32 v1, 0x6000, v0
	v_mul_i32_i24_e32 v0, 0x6000, v0
	v_add_f32_dpp v2, v2, v2 quad_perm:[1,0,3,2] row_mask:0xf bank_mask:0xf bound_ctrl:1
	v_lshl_add_u64 v[0:1], s[64:65], 0, v[0:1]
	v_lshl_add_u64 v[68:69], v[0:1], 0, s[70:71]
	v_add_f32_dpp v2, v2, v2 quad_perm:[2,3,0,1] row_mask:0xf bank_mask:0xf bound_ctrl:1
	v_ashrrev_i32_e32 v57, 31, v56
	v_lshlrev_b64 v[78:79], 11, v[56:57]
	v_add_f32_dpp v2, v2, v2 row_half_mirror row_mask:0xf bank_mask:0xf bound_ctrl:1
	v_lshl_add_u64 v[56:57], v[0:1], 0, v[12:13]
	v_mov_b32_e32 v51, v13
	v_add_f32_dpp v2, v2, v2 row_mirror row_mask:0xf bank_mask:0xf bound_ctrl:1
	v_mov_b32_e32 v53, v13
	v_readlane_b32 s2, v2, 16
	v_readlane_b32 s3, v2, 48
	v_readlane_b32 s0, v2, 0
	v_readlane_b32 s1, v2, 32
	v_mov_b32_e32 v2, s2
	v_mov_b32_e32 v3, s3
	v_pk_add_f32 v[2:3], s[0:1], v[2:3]
	v_mov_b32_e32 v55, v13
	v_add_f32_e32 v2, v2, v3
	v_fmamk_f32 v2, v2, 0x3a800000, v17
	v_cmp_gt_f32_e64 s[0:1], s91, v2
	v_mul_f32_e32 v3, 0x4b800000, v2
	s_nop 0
	v_cndmask_b32_e64 v2, v2, v3, s[0:1]
	v_rsq_f32_e32 v2, v2
	s_nop 0
	v_mul_f32_e32 v3, 0x45800000, v2
	v_cndmask_b32_e64 v58, v2, v3, s[0:1]
	v_lshl_add_u64 v[2:3], v[68:69], 0, v[12:13]
	global_load_dwordx4 v[8:11], v[18:19], off
	global_load_dwordx4 v[4:7], v[2:3], off
	s_nop 0
	global_load_dwordx4 v[0:3], v[56:57], off
	global_load_dwordx4 v[96:99], v[22:23], off
	v_mov_b32_e32 v132, v50
	v_mov_b32_e32 v133, v13
	v_lshl_add_u64 v[134:135], v[68:69], 0, v[132:133]
	global_load_dwordx4 v[100:103], v[134:135], off
	global_load_dwordx4 v[104:107], v[56:57], off offset:1024
	global_load_dwordx4 v[108:111], v[26:27], off
	v_mov_b32_e32 v132, v52
	v_mov_b32_e32 v133, v13
	v_lshl_add_u64 v[134:135], v[68:69], 0, v[132:133]
	global_load_dwordx4 v[112:115], v[134:135], off
	global_load_dwordx4 v[116:119], v[56:57], off offset:2048
	global_load_dwordx4 v[120:123], v[30:31], off
	v_mov_b32_e32 v132, v54
	v_mov_b32_e32 v133, v13
	v_lshl_add_u64 v[134:135], v[68:69], 0, v[132:133]
	global_load_dwordx4 v[124:127], v[134:135], off
	global_load_dwordx4 v[128:131], v[56:57], off offset:3072
	v_pk_mul_f32 v[76:77], v[58:59], v[76:77] op_sel_hi:[0,1]
	v_pk_mul_f32 v[74:75], v[58:59], v[74:75] op_sel_hi:[0,1]
	v_pk_mul_f32 v[70:71], v[58:59], v[70:71] op_sel_hi:[0,1]
	v_cmp_gt_i32_e64 s[0:1], s86, v25
	s_waitcnt vmcnt(0) lgkmcnt(0)
	v_mov_b32_e32 v80, v8
	v_mov_b32_e32 v81, v10
	v_pk_mul_f32 v[76:77], v[80:81], v[76:77]
	v_mov_b32_e32 v80, v4
	v_mov_b32_e32 v81, v6
	v_pk_add_f32 v[80:81], v[80:81], 1.0 op_sel_hi:[1,0]
	v_mov_b32_e32 v82, v0
	v_mov_b32_e32 v83, v2
	v_mov_b32_e32 v10, v9
	v_mov_b32_e32 v6, v5
	v_pk_fma_f32 v[76:77], v[80:81], v[76:77], v[82:83]
	v_pk_mul_f32 v[8:9], v[10:11], v[74:75]
	v_pk_add_f32 v[4:5], v[6:7], 1.0 op_sel_hi:[1,0]
	v_mov_b32_e32 v2, v1
	v_pk_fma_f32 v[0:1], v[4:5], v[8:9], v[2:3]
	v_and_b32_sdwa v3, v76, v21 dst_sel:DWORD dst_unused:UNUSED_PAD src0_sel:WORD_1 src1_sel:DWORD
	v_add3_u32 v4, v76, v3, s84
	v_and_b32_sdwa v3, v1, v21 dst_sel:DWORD dst_unused:UNUSED_PAD src0_sel:WORD_1 src1_sel:DWORD
	v_and_b32_sdwa v5, v0, v21 dst_sel:DWORD dst_unused:UNUSED_PAD src0_sel:WORD_1 src1_sel:DWORD
	v_and_b32_sdwa v2, v77, v21 dst_sel:DWORD dst_unused:UNUSED_PAD src0_sel:WORD_1 src1_sel:DWORD
	v_add3_u32 v1, v1, v3, s84
	v_add3_u32 v0, v0, v5, s84
	v_add3_u32 v2, v77, v2, s84
	v_and_b32_e32 v1, 0xffff0000, v1
	v_and_b32_e32 v0, 0xffff0000, v0
	v_or_b32_sdwa v3, v1, v2 dst_sel:DWORD dst_unused:UNUSED_PAD src0_sel:DWORD src1_sel:WORD_1
	v_or_b32_sdwa v2, v0, v4 dst_sel:DWORD dst_unused:UNUSED_PAD src0_sel:DWORD src1_sel:WORD_1
	v_lshl_add_u64 v[0:1], v[32:33], 0, v[78:79]
	global_store_dwordx2 v[0:1], v[2:3], off
	v_lshl_add_u64 v[6:7], v[68:69], 0, v[50:51]
	s_nop 0
	s_nop 0
	v_pk_mul_f32 v[10:11], v[58:59], v[72:73] op_sel_hi:[0,1]
	s_waitcnt lgkmcnt(0)
	v_mov_b32_e32 v2, v96
	v_mov_b32_e32 v3, v97
	v_mov_b32_e32 v4, v98
	v_mov_b32_e32 v5, v99
	v_mov_b32_e32 v6, v100
	v_mov_b32_e32 v7, v101
	v_mov_b32_e32 v8, v102
	v_mov_b32_e32 v9, v103
	v_mov_b32_e32 v74, v104
	v_mov_b32_e32 v75, v105
	v_mov_b32_e32 v76, v106
	v_mov_b32_e32 v77, v107
	v_mov_b32_e32 v72, v2
	v_mov_b32_e32 v73, v4
	v_pk_mul_f32 v[10:11], v[10:11], v[72:73]
	v_mov_b32_e32 v73, v8
	v_mov_b32_e32 v4, v3
	v_mov_b32_e32 v8, v7
	v_mov_b32_e32 v72, v6
	v_mov_b32_e32 v79, v76
	v_pk_mul_f32 v[2:3], v[70:71], v[4:5]
	v_pk_add_f32 v[4:5], v[8:9], 1.0 op_sel_hi:[1,0]
	v_mov_b32_e32 v76, v75
	v_pk_add_f32 v[72:73], v[72:73], 1.0 op_sel_hi:[1,0]
	v_mov_b32_e32 v78, v74
	v_pk_fma_f32 v[2:3], v[2:3], v[4:5], v[76:77]
	v_pk_fma_f32 v[10:11], v[10:11], v[72:73], v[78:79]
	v_and_b32_sdwa v6, v3, v21 dst_sel:DWORD dst_unused:UNUSED_PAD src0_sel:WORD_1 src1_sel:DWORD
	v_and_b32_sdwa v7, v2, v21 dst_sel:DWORD dst_unused:UNUSED_PAD src0_sel:WORD_1 src1_sel:DWORD
	v_and_b32_sdwa v4, v11, v21 dst_sel:DWORD dst_unused:UNUSED_PAD src0_sel:WORD_1 src1_sel:DWORD
	v_and_b32_sdwa v5, v10, v21 dst_sel:DWORD dst_unused:UNUSED_PAD src0_sel:WORD_1 src1_sel:DWORD
	v_add3_u32 v3, v3, v6, s84
	v_add3_u32 v2, v2, v7, s84
	v_add3_u32 v5, v10, v5, s84
	v_add3_u32 v4, v11, v4, s84
	v_and_b32_e32 v3, 0xffff0000, v3
	v_and_b32_e32 v2, 0xffff0000, v2
	v_or_b32_sdwa v3, v3, v4 dst_sel:DWORD dst_unused:UNUSED_PAD src0_sel:DWORD src1_sel:WORD_1
	v_or_b32_sdwa v2, v2, v5 dst_sel:DWORD dst_unused:UNUSED_PAD src0_sel:DWORD src1_sel:WORD_1
	global_store_dwordx2 v[0:1], v[2:3], off offset:512
	v_lshl_add_u64 v[6:7], v[68:69], 0, v[52:53]
	s_nop 0
	s_nop 0
	v_mov_b32_e32 v10, v64
	v_mov_b32_e32 v11, v66
	v_pk_mul_f32 v[10:11], v[58:59], v[10:11] op_sel_hi:[0,1]
	v_mov_b32_e32 v66, v65
	s_waitcnt lgkmcnt(0)
	v_mov_b32_e32 v2, v108
	v_mov_b32_e32 v3, v109
	v_mov_b32_e32 v4, v110
	v_mov_b32_e32 v5, v111
	v_mov_b32_e32 v6, v112
	v_mov_b32_e32 v7, v113
	v_mov_b32_e32 v8, v114
	v_mov_b32_e32 v9, v115
	v_mov_b32_e32 v70, v116
	v_mov_b32_e32 v71, v117
	v_mov_b32_e32 v72, v118
	v_mov_b32_e32 v73, v119
	v_mov_b32_e32 v74, v2
	v_mov_b32_e32 v75, v4
	v_pk_mul_f32 v[10:11], v[10:11], v[74:75]
	v_mov_b32_e32 v74, v6
	v_mov_b32_e32 v75, v8
	v_pk_add_f32 v[74:75], v[74:75], 1.0 op_sel_hi:[1,0]
	v_mov_b32_e32 v76, v70
	v_mov_b32_e32 v77, v72
	v_pk_fma_f32 v[10:11], v[10:11], v[74:75], v[76:77]
	v_mov_b32_e32 v74, v62
	v_mov_b32_e32 v75, v60
	v_pk_mul_f32 v[74:75], v[58:59], v[74:75] op_sel_hi:[0,1]
	v_mov_b32_e32 v4, v3
	v_mov_b32_e32 v8, v7
	v_pk_mul_f32 v[2:3], v[74:75], v[4:5]
	v_pk_add_f32 v[4:5], v[8:9], 1.0 op_sel_hi:[1,0]
	v_mov_b32_e32 v72, v71
	v_pk_fma_f32 v[2:3], v[2:3], v[4:5], v[72:73]
	v_and_b32_sdwa v4, v11, v21 dst_sel:DWORD dst_unused:UNUSED_PAD src0_sel:WORD_1 src1_sel:DWORD
	v_and_b32_sdwa v6, v3, v21 dst_sel:DWORD dst_unused:UNUSED_PAD src0_sel:WORD_1 src1_sel:DWORD
	v_and_b32_sdwa v7, v2, v21 dst_sel:DWORD dst_unused:UNUSED_PAD src0_sel:WORD_1 src1_sel:DWORD
	v_and_b32_sdwa v5, v10, v21 dst_sel:DWORD dst_unused:UNUSED_PAD src0_sel:WORD_1 src1_sel:DWORD
	v_add3_u32 v3, v3, v6, s84
	v_add3_u32 v2, v2, v7, s84
	v_add3_u32 v5, v10, v5, s84
	v_add3_u32 v4, v11, v4, s84
	v_and_b32_e32 v3, 0xffff0000, v3
	v_and_b32_e32 v2, 0xffff0000, v2
	v_or_b32_sdwa v3, v3, v4 dst_sel:DWORD dst_unused:UNUSED_PAD src0_sel:DWORD src1_sel:WORD_1
	v_or_b32_sdwa v2, v2, v5 dst_sel:DWORD dst_unused:UNUSED_PAD src0_sel:DWORD src1_sel:WORD_1
	global_store_dwordx2 v[0:1], v[2:3], off offset:1024
	v_lshl_add_u64 v[6:7], v[68:69], 0, v[54:55]
	s_nop 0
	s_nop 0
	v_pk_mul_f32 v[10:11], v[58:59], v[66:67] op_sel_hi:[0,1]
	v_mov_b32_e32 v60, v63
	s_waitcnt lgkmcnt(0)
	v_mov_b32_e32 v2, v120
	v_mov_b32_e32 v3, v121
	v_mov_b32_e32 v4, v122
	v_mov_b32_e32 v5, v123
	v_mov_b32_e32 v6, v124
	v_mov_b32_e32 v7, v125
	v_mov_b32_e32 v8, v126
	v_mov_b32_e32 v9, v127
	v_mov_b32_e32 v68, v128
	v_mov_b32_e32 v69, v129
	v_mov_b32_e32 v70, v130
	v_mov_b32_e32 v71, v131
	v_mov_b32_e32 v56, v2
	v_mov_b32_e32 v57, v4
	v_pk_mul_f32 v[10:11], v[10:11], v[56:57]
	v_mov_b32_e32 v56, v6
	v_mov_b32_e32 v57, v8
	v_pk_add_f32 v[56:57], v[56:57], 1.0 op_sel_hi:[1,0]
	v_mov_b32_e32 v64, v68
	v_mov_b32_e32 v65, v70
	v_pk_fma_f32 v[10:11], v[10:11], v[56:57], v[64:65]
	v_pk_mul_f32 v[56:57], v[58:59], v[60:61] op_sel_hi:[0,1]
	v_mov_b32_e32 v4, v3
	v_mov_b32_e32 v8, v7
	v_pk_mul_f32 v[2:3], v[56:57], v[4:5]
	v_pk_add_f32 v[4:5], v[8:9], 1.0 op_sel_hi:[1,0]
	v_mov_b32_e32 v70, v69
	v_pk_fma_f32 v[2:3], v[2:3], v[4:5], v[70:71]
	v_and_b32_sdwa v4, v11, v21 dst_sel:DWORD dst_unused:UNUSED_PAD src0_sel:WORD_1 src1_sel:DWORD
	v_and_b32_sdwa v6, v3, v21 dst_sel:DWORD dst_unused:UNUSED_PAD src0_sel:WORD_1 src1_sel:DWORD
	v_and_b32_sdwa v7, v2, v21 dst_sel:DWORD dst_unused:UNUSED_PAD src0_sel:WORD_1 src1_sel:DWORD
	v_and_b32_sdwa v5, v10, v21 dst_sel:DWORD dst_unused:UNUSED_PAD src0_sel:WORD_1 src1_sel:DWORD
	v_add3_u32 v3, v3, v6, s84
	v_add3_u32 v2, v2, v7, s84
	v_add3_u32 v5, v10, v5, s84
	v_add3_u32 v4, v11, v4, s84
	v_and_b32_e32 v3, 0xffff0000, v3
	v_and_b32_e32 v2, 0xffff0000, v2
	v_or_b32_sdwa v3, v3, v4 dst_sel:DWORD dst_unused:UNUSED_PAD src0_sel:DWORD src1_sel:WORD_1
	v_or_b32_sdwa v2, v2, v5 dst_sel:DWORD dst_unused:UNUSED_PAD src0_sel:DWORD src1_sel:WORD_1
	global_store_dwordx2 v[0:1], v[2:3], off offset:1536
	s_and_b64 exec, exec, s[0:1]
	s_cbranch_execz .LBB0_1195
	v_and_b32_e32 v64, 0xffff0000, v48
	v_and_b32_e32 v60, 0xffff0000, v46
	v_lshlrev_b32_e32 v66, 16, v48
	v_lshlrev_b32_e32 v62, 16, v46
	v_mov_b32_e32 v4, v64
	v_mov_b32_e32 v5, v60
	v_lshlrev_b32_e32 v67, 16, v49
	v_lshlrev_b32_e32 v63, 16, v47
	v_mov_b32_e32 v2, v66
	v_mov_b32_e32 v3, v62
	v_pk_mul_f32 v[4:5], v[4:5], v[4:5]
	v_and_b32_e32 v65, 0xffff0000, v49
	v_and_b32_e32 v61, 0xffff0000, v47
	v_pk_fma_f32 v[2:3], v[2:3], v[2:3], v[4:5]
	v_mov_b32_e32 v4, v67
	v_mov_b32_e32 v5, v63
	v_and_b32_e32 v47, 0xffff0000, v44
	v_and_b32_e32 v46, 0xffff0000, v42
	v_pk_fma_f32 v[2:3], v[4:5], v[4:5], v[2:3]
	v_mov_b32_e32 v4, v65
	v_mov_b32_e32 v5, v61
	v_lshlrev_b32_e32 v49, 16, v44
	v_lshlrev_b32_e32 v48, 16, v42
	v_pk_fma_f32 v[2:3], v[4:5], v[4:5], v[2:3]
	v_pk_mul_f32 v[4:5], v[46:47], v[46:47]
	v_lshlrev_b32_e32 v57, 16, v45
	v_lshlrev_b32_e32 v56, 16, v43
	v_pk_fma_f32 v[4:5], v[48:49], v[48:49], v[4:5]
	v_and_b32_e32 v45, 0xffff0000, v45
	v_and_b32_e32 v44, 0xffff0000, v43
	v_pk_fma_f32 v[4:5], v[56:57], v[56:57], v[4:5]
	v_add_f32_e32 v2, v2, v3
	v_pk_fma_f32 v[4:5], v[44:45], v[44:45], v[4:5]
	v_cndmask_b32_e64 v0, v15, 16, vcc
	v_add_f32_e32 v2, v2, v4
	v_add_f32_e32 v2, v2, v5
	v_mul_hi_i32_i24_e32 v1, 0x6000, v0
	v_mul_i32_i24_e32 v0, 0x6000, v0
	v_add_f32_dpp v2, v2, v2 quad_perm:[1,0,3,2] row_mask:0xf bank_mask:0xf bound_ctrl:1
	v_lshl_add_u64 v[0:1], s[64:65], 0, v[0:1]
	v_lshl_add_u64 v[58:59], v[0:1], 0, s[70:71]
	v_add_f32_dpp v2, v2, v2 quad_perm:[2,3,0,1] row_mask:0xf bank_mask:0xf bound_ctrl:1
	v_ashrrev_i32_e32 v41, 31, v40
	v_lshlrev_b64 v[68:69], 11, v[40:41]
	v_add_f32_dpp v2, v2, v2 row_half_mirror row_mask:0xf bank_mask:0xf bound_ctrl:1
	v_lshl_add_u64 v[40:41], v[0:1], 0, v[12:13]
	s_nop 0
	v_add_f32_dpp v2, v2, v2 row_mirror row_mask:0xf bank_mask:0xf bound_ctrl:1
	s_nop 0
	v_readlane_b32 s2, v2, 16
	v_readlane_b32 s3, v2, 48
	v_readlane_b32 s0, v2, 0
	v_readlane_b32 s1, v2, 32
	v_mov_b32_e32 v2, s2
	v_mov_b32_e32 v3, s3
	v_pk_add_f32 v[2:3], s[0:1], v[2:3]
	s_nop 0
	v_add_f32_e32 v2, v2, v3
	v_fmamk_f32 v2, v2, 0x3a800000, v17
	v_cmp_gt_f32_e32 vcc, s91, v2
	v_mul_f32_e32 v3, 0x4b800000, v2
	s_nop 0
	v_cndmask_b32_e32 v2, v2, v3, vcc
	v_rsq_f32_e32 v2, v2
	s_nop 0
	v_mul_f32_e32 v3, 0x45800000, v2
	v_cndmask_b32_e32 v42, v2, v3, vcc
	v_lshl_add_u64 v[2:3], v[58:59], 0, v[12:13]
	global_load_dwordx4 v[8:11], v[18:19], off
	global_load_dwordx4 v[4:7], v[2:3], off
	s_nop 0
	global_load_dwordx4 v[0:3], v[40:41], off
	global_load_dwordx4 v[96:99], v[22:23], off
	v_mov_b32_e32 v132, v50
	v_mov_b32_e32 v133, v51
	v_lshl_add_u64 v[134:135], v[58:59], 0, v[132:133]
	global_load_dwordx4 v[100:103], v[134:135], off
	global_load_dwordx4 v[104:107], v[40:41], off offset:1024
	global_load_dwordx4 v[108:111], v[26:27], off
	v_mov_b32_e32 v132, v52
	v_mov_b32_e32 v133, v53
	v_lshl_add_u64 v[134:135], v[58:59], 0, v[132:133]
	global_load_dwordx4 v[112:115], v[134:135], off
	global_load_dwordx4 v[116:119], v[40:41], off offset:2048
	global_load_dwordx4 v[120:123], v[30:31], off
	v_mov_b32_e32 v132, v54
	v_mov_b32_e32 v133, v13
	v_lshl_add_u64 v[134:135], v[58:59], 0, v[132:133]
	global_load_dwordx4 v[124:127], v[134:135], off
	global_load_dwordx4 v[128:131], v[40:41], off offset:3072
	v_pk_mul_f32 v[66:67], v[42:43], v[66:67] op_sel_hi:[0,1]
	v_pk_mul_f32 v[64:65], v[42:43], v[64:65] op_sel_hi:[0,1]
	s_waitcnt vmcnt(0) lgkmcnt(0)
	v_mov_b32_e32 v70, v8
	v_mov_b32_e32 v71, v10
	v_pk_mul_f32 v[66:67], v[70:71], v[66:67]
	v_mov_b32_e32 v70, v4
	v_mov_b32_e32 v71, v6
	v_pk_add_f32 v[70:71], v[70:71], 1.0 op_sel_hi:[1,0]
	v_mov_b32_e32 v72, v0
	v_mov_b32_e32 v73, v2
	v_mov_b32_e32 v10, v9
	v_mov_b32_e32 v6, v5
	v_pk_fma_f32 v[66:67], v[70:71], v[66:67], v[72:73]
	v_pk_mul_f32 v[8:9], v[10:11], v[64:65]
	v_pk_add_f32 v[4:5], v[6:7], 1.0 op_sel_hi:[1,0]
	v_mov_b32_e32 v2, v1
	v_pk_fma_f32 v[0:1], v[4:5], v[8:9], v[2:3]
	v_and_b32_sdwa v3, v66, v21 dst_sel:DWORD dst_unused:UNUSED_PAD src0_sel:WORD_1 src1_sel:DWORD
	v_add3_u32 v4, v66, v3, s84
	v_and_b32_sdwa v3, v1, v21 dst_sel:DWORD dst_unused:UNUSED_PAD src0_sel:WORD_1 src1_sel:DWORD
	v_and_b32_sdwa v5, v0, v21 dst_sel:DWORD dst_unused:UNUSED_PAD src0_sel:WORD_1 src1_sel:DWORD
	v_and_b32_sdwa v2, v67, v21 dst_sel:DWORD dst_unused:UNUSED_PAD src0_sel:WORD_1 src1_sel:DWORD
	v_add3_u32 v1, v1, v3, s84
	v_add3_u32 v0, v0, v5, s84
	v_add3_u32 v2, v67, v2, s84
	v_and_b32_e32 v1, 0xffff0000, v1
	v_and_b32_e32 v0, 0xffff0000, v0
	v_or_b32_sdwa v3, v1, v2 dst_sel:DWORD dst_unused:UNUSED_PAD src0_sel:DWORD src1_sel:WORD_1
	v_or_b32_sdwa v2, v0, v4 dst_sel:DWORD dst_unused:UNUSED_PAD src0_sel:DWORD src1_sel:WORD_1
	v_lshl_add_u64 v[0:1], v[32:33], 0, v[68:69]
	global_store_dwordx2 v[0:1], v[2:3], off
	v_lshl_add_u64 v[6:7], v[58:59], 0, v[50:51]
	s_nop 0
	s_nop 0
	v_pk_mul_f32 v[10:11], v[42:43], v[62:63] op_sel_hi:[0,1]
	s_waitcnt lgkmcnt(0)
	v_mov_b32_e32 v2, v96
	v_mov_b32_e32 v3, v97
	v_mov_b32_e32 v4, v98
	v_mov_b32_e32 v5, v99
	v_mov_b32_e32 v6, v100
	v_mov_b32_e32 v7, v101
	v_mov_b32_e32 v8, v102
	v_mov_b32_e32 v9, v103
	v_mov_b32_e32 v64, v104
	v_mov_b32_e32 v65, v105
	v_mov_b32_e32 v66, v106
	v_mov_b32_e32 v67, v107
	v_mov_b32_e32 v50, v2
	v_mov_b32_e32 v51, v4
	v_pk_mul_f32 v[10:11], v[10:11], v[50:51]
	v_mov_b32_e32 v50, v6
	v_mov_b32_e32 v51, v8
	v_pk_add_f32 v[50:51], v[50:51], 1.0 op_sel_hi:[1,0]
	v_mov_b32_e32 v62, v64
	v_mov_b32_e32 v63, v66
	v_pk_fma_f32 v[10:11], v[10:11], v[50:51], v[62:63]
	v_pk_mul_f32 v[50:51], v[42:43], v[60:61] op_sel_hi:[0,1]
	v_mov_b32_e32 v4, v3
	v_mov_b32_e32 v8, v7
	v_pk_mul_f32 v[2:3], v[50:51], v[4:5]
	v_pk_add_f32 v[4:5], v[8:9], 1.0 op_sel_hi:[1,0]
	v_mov_b32_e32 v66, v65
	v_pk_fma_f32 v[2:3], v[2:3], v[4:5], v[66:67]
	v_and_b32_sdwa v4, v11, v21 dst_sel:DWORD dst_unused:UNUSED_PAD src0_sel:WORD_1 src1_sel:DWORD
	v_and_b32_sdwa v6, v3, v21 dst_sel:DWORD dst_unused:UNUSED_PAD src0_sel:WORD_1 src1_sel:DWORD
	v_and_b32_sdwa v7, v2, v21 dst_sel:DWORD dst_unused:UNUSED_PAD src0_sel:WORD_1 src1_sel:DWORD
	v_and_b32_sdwa v5, v10, v21 dst_sel:DWORD dst_unused:UNUSED_PAD src0_sel:WORD_1 src1_sel:DWORD
	v_add3_u32 v3, v3, v6, s84
	v_add3_u32 v2, v2, v7, s84
	v_add3_u32 v5, v10, v5, s84
	v_add3_u32 v4, v11, v4, s84
	v_and_b32_e32 v3, 0xffff0000, v3
	v_and_b32_e32 v2, 0xffff0000, v2
	v_or_b32_sdwa v3, v3, v4 dst_sel:DWORD dst_unused:UNUSED_PAD src0_sel:DWORD src1_sel:WORD_1
	v_or_b32_sdwa v2, v2, v5 dst_sel:DWORD dst_unused:UNUSED_PAD src0_sel:DWORD src1_sel:WORD_1
	global_store_dwordx2 v[0:1], v[2:3], off offset:512
	v_lshl_add_u64 v[6:7], v[58:59], 0, v[52:53]
	s_nop 0
	s_nop 0
	v_mov_b32_e32 v10, v48
	v_mov_b32_e32 v11, v56
	v_pk_mul_f32 v[10:11], v[42:43], v[10:11] op_sel_hi:[0,1]
	v_mov_b32_e32 v56, v49
	s_waitcnt lgkmcnt(0)
	v_mov_b32_e32 v2, v108
	v_mov_b32_e32 v3, v109
	v_mov_b32_e32 v4, v110
	v_mov_b32_e32 v5, v111
	v_mov_b32_e32 v6, v112
	v_mov_b32_e32 v7, v113
	v_mov_b32_e32 v8, v114
	v_mov_b32_e32 v9, v115
	v_mov_b32_e32 v50, v116
	v_mov_b32_e32 v51, v117
	v_mov_b32_e32 v52, v118
	v_mov_b32_e32 v53, v119
	v_mov_b32_e32 v60, v2
	v_mov_b32_e32 v61, v4
	v_pk_mul_f32 v[10:11], v[10:11], v[60:61]
	v_mov_b32_e32 v60, v6
	v_mov_b32_e32 v61, v8
	v_pk_add_f32 v[60:61], v[60:61], 1.0 op_sel_hi:[1,0]
	v_mov_b32_e32 v62, v50
	v_mov_b32_e32 v63, v52
	v_pk_fma_f32 v[10:11], v[10:11], v[60:61], v[62:63]
	v_mov_b32_e32 v60, v46
	v_mov_b32_e32 v61, v44
	v_pk_mul_f32 v[60:61], v[42:43], v[60:61] op_sel_hi:[0,1]
	v_mov_b32_e32 v4, v3
	v_mov_b32_e32 v8, v7
	v_pk_mul_f32 v[2:3], v[60:61], v[4:5]
	v_pk_add_f32 v[4:5], v[8:9], 1.0 op_sel_hi:[1,0]
	v_mov_b32_e32 v52, v51
	v_pk_fma_f32 v[2:3], v[2:3], v[4:5], v[52:53]
	v_and_b32_sdwa v4, v11, v21 dst_sel:DWORD dst_unused:UNUSED_PAD src0_sel:WORD_1 src1_sel:DWORD
	v_and_b32_sdwa v6, v3, v21 dst_sel:DWORD dst_unused:UNUSED_PAD src0_sel:WORD_1 src1_sel:DWORD
	v_and_b32_sdwa v7, v2, v21 dst_sel:DWORD dst_unused:UNUSED_PAD src0_sel:WORD_1 src1_sel:DWORD
	v_and_b32_sdwa v5, v10, v21 dst_sel:DWORD dst_unused:UNUSED_PAD src0_sel:WORD_1 src1_sel:DWORD
	v_add3_u32 v3, v3, v6, s84
	v_add3_u32 v2, v2, v7, s84
	v_add3_u32 v5, v10, v5, s84
	v_add3_u32 v4, v11, v4, s84
	v_and_b32_e32 v3, 0xffff0000, v3
	v_and_b32_e32 v2, 0xffff0000, v2
	v_or_b32_sdwa v3, v3, v4 dst_sel:DWORD dst_unused:UNUSED_PAD src0_sel:DWORD src1_sel:WORD_1
	v_or_b32_sdwa v2, v2, v5 dst_sel:DWORD dst_unused:UNUSED_PAD src0_sel:DWORD src1_sel:WORD_1
	global_store_dwordx2 v[0:1], v[2:3], off offset:1024
	v_lshl_add_u64 v[6:7], v[58:59], 0, v[54:55]
	s_nop 0
	s_nop 0
	v_pk_mul_f32 v[10:11], v[42:43], v[56:57] op_sel_hi:[0,1]
	v_mov_b32_e32 v44, v47
	s_waitcnt lgkmcnt(0)
	v_mov_b32_e32 v2, v120
	v_mov_b32_e32 v3, v121
	v_mov_b32_e32 v4, v122
	v_mov_b32_e32 v5, v123
	v_mov_b32_e32 v6, v124
	v_mov_b32_e32 v7, v125
	v_mov_b32_e32 v8, v126
	v_mov_b32_e32 v9, v127
	v_mov_b32_e32 v50, v128
	v_mov_b32_e32 v51, v129
	v_mov_b32_e32 v52, v130
	v_mov_b32_e32 v53, v131
	v_mov_b32_e32 v40, v2
	v_mov_b32_e32 v41, v4
	v_pk_mul_f32 v[10:11], v[10:11], v[40:41]
	v_mov_b32_e32 v40, v6
	v_mov_b32_e32 v41, v8
	v_pk_add_f32 v[40:41], v[40:41], 1.0 op_sel_hi:[1,0]
	v_mov_b32_e32 v48, v50
	v_mov_b32_e32 v49, v52
	v_pk_fma_f32 v[10:11], v[10:11], v[40:41], v[48:49]
	v_pk_mul_f32 v[40:41], v[42:43], v[44:45] op_sel_hi:[0,1]
	v_mov_b32_e32 v4, v3
	v_mov_b32_e32 v8, v7
	v_pk_mul_f32 v[2:3], v[40:41], v[4:5]
	v_pk_add_f32 v[4:5], v[8:9], 1.0 op_sel_hi:[1,0]
	v_mov_b32_e32 v52, v51
	v_pk_fma_f32 v[2:3], v[2:3], v[4:5], v[52:53]
	v_and_b32_sdwa v4, v11, v21 dst_sel:DWORD dst_unused:UNUSED_PAD src0_sel:WORD_1 src1_sel:DWORD
	v_and_b32_sdwa v6, v3, v21 dst_sel:DWORD dst_unused:UNUSED_PAD src0_sel:WORD_1 src1_sel:DWORD
	v_and_b32_sdwa v7, v2, v21 dst_sel:DWORD dst_unused:UNUSED_PAD src0_sel:WORD_1 src1_sel:DWORD
	v_and_b32_sdwa v5, v10, v21 dst_sel:DWORD dst_unused:UNUSED_PAD src0_sel:WORD_1 src1_sel:DWORD
	v_add3_u32 v3, v3, v6, s84
	v_add3_u32 v2, v2, v7, s84
	v_add3_u32 v5, v10, v5, s84
	v_add3_u32 v4, v11, v4, s84
	v_and_b32_e32 v3, 0xffff0000, v3
	v_and_b32_e32 v2, 0xffff0000, v2
	v_or_b32_sdwa v3, v3, v4 dst_sel:DWORD dst_unused:UNUSED_PAD src0_sel:DWORD src1_sel:WORD_1
	v_or_b32_sdwa v2, v2, v5 dst_sel:DWORD dst_unused:UNUSED_PAD src0_sel:DWORD src1_sel:WORD_1
	global_store_dwordx2 v[0:1], v[2:3], off offset:1536
	s_branch .LBB0_1195
